# FoX tile loop: first two K-fragment LDS reads issued with the decay-bound broadcast read right after the barrier (one LDS round trip less before the first MFMA)
# speedup vs baseline: 1.0097x; 1.0097x over previous
.LBB0_1689:
	s_and_b32 s2, s18, 1
	s_mul_i32 s3, s2, 0x2400
	s_add_i32 s19, s3, 0
	s_mulk_i32 s2, 0xdd00
	s_add_i32 s16, s19, s2
	v_add3_u32 v0, s19, v123, v124
	s_waitcnt vmcnt(1)
	ds_write_b128 v0, v[96:99]
	s_waitcnt vmcnt(0)
	ds_write_b128 v0, v[100:103] offset:18432
	s_and_saveexec_b64 s[2:3], s[0:1]
	v_mul_f32_e32 v121, 0x3fb8aa3b, v220
	v_lshl_add_u32 v0, v110, 2, s16
	ds_write_b32 v0, v121 offset:36864
	s_or_b64 exec, exec, s[2:3]
	v_mov_b32_e32 v0, s16
	s_waitcnt lgkmcnt(0)
	s_barrier
	ds_read_b32 v0, v0 offset:37116
	v_add3_u32 v225, s19, v126, v114
	ds_read_b128 v[240:243], v225
	ds_read_b128 v[244:247], v225 offset:32
	s_waitcnt lgkmcnt(2)
	v_cmp_gt_f32_e32 vcc, v0, v122
	v_mov_b32_e32 v0, 17
	s_cbranch_vccnz .LBB0_1703
	s_cmp_lt_i32 s9, 1
	s_cbranch_scc1 .LBB0_1696
	s_add_i32 s2, s9, -1
	v_mad_u64_u32 v[2:3], s[2:3], s2, v230, v[116:117]
	global_load_dwordx4 v[96:99], v[2:3], off offset:2048
	global_load_dwordx4 v[100:103], v[2:3], off offset:2560
	s_and_saveexec_b64 s[2:3], s[0:1]
	s_cbranch_execz .LBB0_1695
	v_lshl_add_u64 v[2:3], v[118:119], 0, s[94:95]
	v_lshl_add_u64 v[2:3], v[2:3], 4, s[10:11]
	global_load_dword v220, v[2:3], off

.LBB0_1696:
	s_add_i32 s2, s94, 64
	v_cmp_le_i32_e32 vcc, s2, v125
	v_mov_b32_e32 v0, 19
	s_and_saveexec_b64 s[14:15], vcc
	s_cbranch_execz .LBB0_1702
	v_add3_u32 v0, s19, v126, v114
	v_sub_f32_e32 v64, v113, v115
	v_mov_b32_e32 v65, v64
	v_mov_b32_e32 v66, v64
	v_mov_b32_e32 v67, v64
	v_mov_b32_e32 v68, v64
	v_mov_b32_e32 v69, v64
	v_mov_b32_e32 v70, v64
	v_mov_b32_e32 v71, v64
	v_mov_b32_e32 v72, v64
	v_mov_b32_e32 v73, v64
	v_mov_b32_e32 v74, v64
	v_mov_b32_e32 v75, v64
	v_mov_b32_e32 v76, v64
	v_mov_b32_e32 v77, v64
	v_mov_b32_e32 v78, v64
	v_mov_b32_e32 v79, v64
	v_lshl_add_u32 v142, v111, 2, s16
	s_add_i32 s2, s94, 0x7f
	s_waitcnt lgkmcnt(1)
	v_mfma_f32_32x32x16_bf16 v[48:63], v[240:243], v[80:83], v[64:79]
	ds_read_b128 v[2:5], v0 offset:4608
	ds_read_b128 v[10:13], v0 offset:4640
	v_cmp_gt_i32_e32 vcc, s2, v120
	s_waitcnt lgkmcnt(1)
	v_mfma_f32_32x32x16_bf16 v[64:79], v[2:5], v[80:83], v[64:79]
	v_mfma_f32_32x32x16_bf16 v[48:63], v[244:247], v[84:87], v[48:63]
	ds_read_b128 v[2:5], v0 offset:64
	ds_read_b128 v[6:9], v0 offset:96
	s_waitcnt lgkmcnt(2)
	v_mfma_f32_32x32x16_bf16 v[64:79], v[10:13], v[84:87], v[64:79]
	s_waitcnt lgkmcnt(1)
	v_mfma_f32_32x32x16_bf16 v[48:63], v[2:5], v[88:91], v[48:63]
	ds_read_b128 v[2:5], v0 offset:4672
	ds_read_b128 v[104:107], v0 offset:4704
	s_waitcnt lgkmcnt(1)
	v_mfma_f32_32x32x16_bf16 v[64:79], v[2:5], v[88:91], v[64:79]
	v_mfma_f32_32x32x16_bf16 v[48:63], v[6:9], v[92:95], v[48:63]
	ds_read_b128 v[6:9], v142 offset:36960
	ds_read_b128 v[130:133], v142 offset:36928
	ds_read_b128 v[134:137], v142 offset:36864
	ds_read_b128 v[138:141], v142 offset:36896
	s_waitcnt lgkmcnt(4)
	v_mfma_f32_32x32x16_bf16 v[64:79], v[104:107], v[92:95], v[64:79]
	s_waitcnt lgkmcnt(3)
	s_nop 4
	v_sub_f32_e32 v15, v63, v9
	v_sub_f32_e32 v14, v62, v8
	v_sub_f32_e32 v13, v61, v7
	v_sub_f32_e32 v12, v60, v6
	s_waitcnt lgkmcnt(2)
	v_sub_f32_e32 v11, v59, v133
	v_sub_f32_e32 v10, v58, v132
	v_sub_f32_e32 v9, v57, v131
	v_sub_f32_e32 v8, v56, v130
	s_waitcnt lgkmcnt(0)
	v_sub_f32_e32 v7, v55, v141
	v_sub_f32_e32 v6, v54, v140
	ds_read_b128 v[54:57], v142 offset:37088
	ds_read_b128 v[58:61], v142 offset:37056
	ds_read_b128 v[104:107], v142 offset:36992
	ds_read_b128 v[130:133], v142 offset:37024
	v_sub_f32_e32 v5, v53, v139
	v_sub_f32_e32 v4, v52, v138
	v_sub_f32_e32 v3, v51, v137
	v_sub_f32_e32 v2, v50, v136
	v_sub_f32_e32 v53, v49, v135
	v_sub_f32_e32 v0, v48, v134
	s_waitcnt lgkmcnt(3)
	v_sub_f32_e32 v49, v79, v57
	v_sub_f32_e32 v48, v78, v56
	v_sub_f32_e32 v51, v77, v55
	v_sub_f32_e32 v50, v76, v54
	s_waitcnt lgkmcnt(2)
	v_sub_f32_e32 v55, v75, v61
	v_sub_f32_e32 v52, v74, v60
	v_sub_f32_e32 v57, v73, v59
	v_sub_f32_e32 v54, v72, v58
	s_waitcnt lgkmcnt(0)
	v_sub_f32_e32 v59, v71, v133
	v_sub_f32_e32 v56, v70, v132
	v_sub_f32_e32 v61, v69, v131
	v_sub_f32_e32 v58, v68, v130
	v_sub_f32_e32 v63, v67, v107
	v_sub_f32_e32 v60, v66, v106
	v_sub_f32_e32 v65, v65, v105
	v_sub_f32_e32 v62, v64, v104
	s_and_saveexec_b64 s[16:17], vcc
	s_cbranch_execz .LBB0_1699
	v_add_u32_e32 v64, s94, v111
	v_add_u32_e32 v67, 0x60, v64
	v_add_u32_e32 v66, 64, v64
	v_cmp_le_i32_e64 s[2:3], v67, v112
	v_cmp_le_i32_e32 vcc, v66, v112
	s_nop 0
	v_cndmask_b32_e64 v62, v236, v62, s[2:3]
	v_cmp_lt_i32_e64 s[2:3], v66, v112
	v_add_u32_e32 v66, 0x61, v64
	v_cndmask_b32_e32 v0, v236, v0, vcc
	v_cmp_le_i32_e32 vcc, v66, v112
	v_add_u32_e32 v66, 0x42, v64
	v_cndmask_b32_e64 v53, v236, v53, s[2:3]
	v_cndmask_b32_e32 v65, v236, v65, vcc
	v_cmp_le_i32_e32 vcc, v66, v112
	v_add_u32_e32 v66, 0x62, v64
	s_nop 0
	v_cndmask_b32_e32 v2, v236, v2, vcc
	v_cmp_le_i32_e32 vcc, v66, v112
	v_add_u32_e32 v66, 0x43, v64
	s_nop 0
	v_cndmask_b32_e32 v60, v236, v60, vcc
	v_cmp_le_i32_e32 vcc, v66, v112
	v_add_u32_e32 v66, 0x63, v64
	s_nop 0
	v_cndmask_b32_e32 v3, v236, v3, vcc
	v_cmp_le_i32_e32 vcc, v66, v112
	v_add_u32_e32 v66, 0x48, v64
	s_nop 0
	v_cndmask_b32_e32 v63, v236, v63, vcc
	v_cmp_le_i32_e32 vcc, v66, v112
	v_add_u32_e32 v66, 0x68, v64
	s_nop 0
	v_cndmask_b32_e32 v4, v236, v4, vcc
	v_cmp_le_i32_e32 vcc, v66, v112
	v_add_u32_e32 v66, 0x49, v64
	s_nop 0
	v_cndmask_b32_e32 v58, v236, v58, vcc
	v_cmp_le_i32_e32 vcc, v66, v112
	v_add_u32_e32 v66, 0x69, v64
	s_nop 0
	v_cndmask_b32_e32 v5, v236, v5, vcc
	v_cmp_le_i32_e32 vcc, v66, v112
	v_add_u32_e32 v66, 0x4a, v64
	s_nop 0
	v_cndmask_b32_e32 v61, v236, v61, vcc
	v_cmp_le_i32_e32 vcc, v66, v112
	v_add_u32_e32 v66, 0x6a, v64
	s_nop 0
	v_cndmask_b32_e32 v6, v236, v6, vcc
	v_cmp_le_i32_e32 vcc, v66, v112
	v_add_u32_e32 v66, 0x4b, v64
	s_nop 0
	v_cndmask_b32_e32 v56, v236, v56, vcc
	v_cmp_le_i32_e32 vcc, v66, v112
	v_add_u32_e32 v66, 0x6b, v64
	s_nop 0
	v_cndmask_b32_e32 v7, v236, v7, vcc
	v_cmp_le_i32_e32 vcc, v66, v112
	v_add_u32_e32 v66, 0x50, v64
	s_nop 0
	v_cndmask_b32_e32 v59, v236, v59, vcc
	v_cmp_le_i32_e32 vcc, v66, v112
	v_add_u32_e32 v66, 0x70, v64
	s_nop 0
	v_cndmask_b32_e32 v8, v236, v8, vcc
	v_cmp_le_i32_e32 vcc, v66, v112
	v_add_u32_e32 v66, 0x51, v64
	s_nop 0
	v_cndmask_b32_e32 v54, v236, v54, vcc
	v_cmp_le_i32_e32 vcc, v66, v112
	v_add_u32_e32 v66, 0x71, v64
	s_nop 0
	v_cndmask_b32_e32 v9, v236, v9, vcc
	v_cmp_le_i32_e32 vcc, v66, v112
	v_add_u32_e32 v66, 0x52, v64
	s_nop 0
	v_cndmask_b32_e32 v57, v236, v57, vcc
	v_cmp_le_i32_e32 vcc, v66, v112
	v_add_u32_e32 v66, 0x72, v64
	s_nop 0
	v_cndmask_b32_e32 v10, v236, v10, vcc
	v_cmp_le_i32_e32 vcc, v66, v112
	v_add_u32_e32 v66, 0x53, v64
	s_nop 0
	v_cndmask_b32_e32 v52, v236, v52, vcc
	v_cmp_le_i32_e32 vcc, v66, v112
	v_add_u32_e32 v66, 0x73, v64
	s_nop 0
	v_cndmask_b32_e32 v11, v236, v11, vcc
	v_cmp_le_i32_e32 vcc, v66, v112
	v_add_u32_e32 v66, 0x58, v64
	s_nop 0
	v_cndmask_b32_e32 v55, v236, v55, vcc
	v_cmp_le_i32_e32 vcc, v66, v112
	v_add_u32_e32 v66, 0x78, v64
	s_nop 0
	v_cndmask_b32_e32 v12, v236, v12, vcc
	v_cmp_le_i32_e32 vcc, v66, v112
	v_add_u32_e32 v66, 0x59, v64
	s_nop 0
	v_cndmask_b32_e32 v50, v236, v50, vcc
	v_cmp_le_i32_e32 vcc, v66, v112
	v_add_u32_e32 v66, 0x79, v64
	s_nop 0
	v_cndmask_b32_e32 v13, v236, v13, vcc
	v_cmp_le_i32_e32 vcc, v66, v112
	v_add_u32_e32 v66, 0x5a, v64
	s_nop 0
	v_cndmask_b32_e32 v51, v236, v51, vcc
	v_cmp_le_i32_e32 vcc, v66, v112
	v_add_u32_e32 v66, 0x7a, v64
	s_nop 0
	v_cndmask_b32_e32 v14, v236, v14, vcc
	v_cmp_le_i32_e32 vcc, v66, v112
	v_add_u32_e32 v66, 0x5b, v64
	v_add_u32_e32 v64, 0x7b, v64
	v_cndmask_b32_e32 v48, v236, v48, vcc
	v_cmp_le_i32_e32 vcc, v66, v112
	s_nop 1
	v_cndmask_b32_e32 v15, v236, v15, vcc
	v_cmp_le_i32_e32 vcc, v64, v112
	s_nop 1
	v_cndmask_b32_e32 v49, v236, v49, vcc
